# baseline (speedup 1.0000x reference)
; __device__ __forceinline__ void sb_decode(int idx, int& b, int& h, int& qb) {
;   if (gridDim.x == 256) {
;     const int r = idx >> 8, bid = idx & 255, k = r * 32 + (bid >> 3);
;     b = bid & 7;
;     h = k & 7;
;     qb = k >> 3;
;     return;
;   }
;   const int r = idx >> 8, j = idx & 255, g = j >> 6, bh = j & 63;
;   qb = (r & 1) ? (12 - 4 * r + g) : (15 - 4 * r - g);
;   b = bh >> 3;
;   h = bh & 7;
; }
.LBB0_375:
	s_and_b32 s9, s9, 7
	v_lshl_add_u32 v3, s9, 12, v162
	v_mov_b64_e32 v[84:85], s[30:31]
	v_mad_i64_i32 v[84:85], s[10:11], v3, s88, v[84:85]
	s_lshl_b32 s6, s6, 6
	s_and_b32 s10, s6, 0x1c0
	s_lshl_b32 s6, s10, 1
	s_mov_b32 s7, s52
	v_lshl_add_u64 v[84:85], v[84:85], 0, s[6:7]
	v_lshlrev_b32_e32 v88, 1, v168
	v_mov_b32_e32 v89, v2
	v_lshl_add_u64 v[84:85], v[84:85], 0, v[88:89]
	s_mov_b64 s[6:7], 0xb900400
	v_lshl_add_u64 v[84:85], v[84:85], 0, s[6:7]
	s_lshl_b32 s6, s9, 9
	s_or_b32 s6, s10, s6
	v_add_u32_e32 v88, s6, v162
	s_lshl_b32 s8, s14, 8
	v_ashrrev_i32_e32 v89, 31, v88
	v_lshlrev_b64 v[88:89], 13, v[88:89]
	s_cmp_gt_i32 s14, -1
	s_cselect_b64 s[10:11], -1, 0
	s_cmp_lt_i32 s14, 0
	v_lshl_add_u64 v[88:89], v[174:175], 0, v[88:89]
	s_cbranch_scc1 .LBB0_377
	s_or_b32 s6, s8, 0xc0
	s_mov_b32 s9, s52
	v_mad_u64_u32 v[8:9], s[6:7], s6, v161, v[84:85]
	v_lshl_add_u64 v[10:11], s[8:9], 1, v[88:89]
	global_load_dwordx4 v[12:15], v[8:9], off nt
	s_nop 0
	global_load_dwordx4 v[8:11], v[10:11], off offset:384 nt
.LBB0_377:
	v_cndmask_b32_e64 v3, 0, 1, s[10:11]
	v_cmp_ne_u32_e64 s[6:7], 1, v3
	s_andn2_b64 vcc, exec, s[10:11]
	s_cbranch_vccnz .LBB0_379
	s_or_b32 s9, s8, 0x80
	v_mad_u64_u32 v[16:17], s[10:11], s9, v161, v[84:85]
	s_mov_b32 s9, s52
	v_lshl_add_u64 v[18:19], s[8:9], 1, v[88:89]
	global_load_dwordx4 v[20:23], v[16:17], off nt
	s_nop 0
	global_load_dwordx4 v[16:19], v[18:19], off offset:256 nt
.LBB0_379:
	s_and_b64 vcc, exec, s[6:7]
	s_cbranch_vccnz .LBB0_381
	s_or_b32 s9, s8, 64
	v_mad_u64_u32 v[24:25], s[10:11], s9, v161, v[84:85]
	s_mov_b32 s9, s52
	v_lshl_add_u64 v[26:27], s[8:9], 1, v[88:89]
	global_load_dwordx4 v[28:31], v[24:25], off nt
	s_nop 0
	global_load_dwordx4 v[24:27], v[26:27], off offset:128 nt
.LBB0_381:
	s_and_b64 vcc, exec, s[6:7]
	s_cbranch_vccnz .LBB0_383
	s_mov_b32 s9, s52
	v_mad_u64_u32 v[32:33], s[6:7], s8, v161, v[84:85]
	v_lshl_add_u64 v[36:37], s[8:9], 1, v[88:89]
	global_load_dwordx4 v[32:35], v[32:33], off nt
	s_nop 0
	global_load_dwordx4 v[36:39], v[36:37], off nt
.LBB0_383:
	s_cmp_gt_i32 s14, 0
	s_cselect_b64 s[10:11], -1, 0
	s_cmp_lt_i32 s14, 1
	s_cbranch_scc1 .LBB0_385
	s_sub_i32 s6, s8, 64
	s_mov_b32 s7, s52
	v_mad_u64_u32 v[40:41], s[14:15], s6, v161, v[84:85]
	v_lshl_add_u64 v[44:45], s[6:7], 1, v[88:89]
	global_load_dwordx4 v[40:43], v[40:41], off nt
	s_nop 0
	global_load_dwordx4 v[44:47], v[44:45], off nt
.LBB0_385:
	v_cndmask_b32_e64 v3, 0, 1, s[10:11]
	v_cmp_ne_u32_e64 s[6:7], 1, v3
	s_andn2_b64 vcc, exec, s[10:11]
	s_cbranch_vccnz .LBB0_387
	s_add_i32 s10, s8, 0xffffff80
	s_mov_b32 s11, s52
	v_mad_u64_u32 v[48:49], s[14:15], s10, v161, v[84:85]
	v_lshl_add_u64 v[52:53], s[10:11], 1, v[88:89]
	global_load_dwordx4 v[48:51], v[48:49], off nt
	s_nop 0
	global_load_dwordx4 v[52:55], v[52:53], off nt
.LBB0_387:
	s_and_b64 vcc, exec, s[6:7]
	s_cbranch_vccnz .LBB0_389
	s_add_i32 s6, s8, 0xffffff40
	s_mov_b32 s7, s52
	v_mad_u64_u32 v[84:85], s[8:9], s6, v161, v[84:85]
	v_lshl_add_u64 v[60:61], s[6:7], 1, v[88:89]
	global_load_dwordx4 v[56:59], v[84:85], off nt
	s_nop 0
	global_load_dwordx4 v[60:63], v[60:61], off nt
